# speedup vs baseline: 1.0054x; 1.0036x over previous
.LBB0_654:
	v_cvt_pk_bf16_f32 v58, v152, v154
	v_cvt_pk_bf16_f32 v59, v153, v155
	v_cvt_pk_bf16_f32 v60, v156, v158
	v_cvt_pk_bf16_f32 v61, v157, v159
	s_waitcnt lgkmcnt(8)
	v_cvt_pk_bf16_f32 v50, v50, v52
	v_cvt_pk_bf16_f32 v51, v51, v53
	v_mfma_f32_32x32x16_bf16 v[16:31], v[140:143], v[58:61], v[16:31]
	v_cvt_pk_bf16_f32 v52, v54, v56
	v_cvt_pk_bf16_f32 v53, v55, v57
	v_cvt_pk_bf16_f32 v32, v32, v48
	v_cvt_pk_bf16_f32 v33, v33, v49
	v_cvt_pk_bf16_f32 v34, v34, v36
	v_cvt_pk_bf16_f32 v35, v35, v37
	v_cvt_pk_bf16_f32 v36, v38, v40
	v_mfma_f32_32x32x16_bf16 v[0:15], v[112:115], v[58:61], v[0:15]
	v_cvt_pk_bf16_f32 v37, v39, v41
	v_cvt_pk_bf16_f32 v38, v42, v44
	v_cvt_pk_bf16_f32 v39, v43, v45
	s_and_b64 vcc, exec, s[10:11]
	v_mfma_f32_32x32x16_bf16 v[16:31], v[136:139], v[50:53], v[16:31]
	s_cbranch_vccnz .Lgq_pk1
	s_add_i32 s12, s7, 2
	s_and_b32 s12, s12, 3
	s_mulk_i32 s12, 0x5000
	s_add_i32 s12, s5, s12
	s_mov_b32 m0, s12
	s_nop 0
	global_load_lds_dwordx4 v[148:149], off

.LBB0_687:
	v_cvt_pk_bf16_f32 v58, v174, v176
	v_cvt_pk_bf16_f32 v59, v175, v177
	v_cvt_pk_bf16_f32 v60, v178, v180
	v_cvt_pk_bf16_f32 v61, v179, v181
	s_waitcnt lgkmcnt(8)
	v_cvt_pk_bf16_f32 v50, v50, v52
	v_cvt_pk_bf16_f32 v51, v51, v53
	v_mfma_f32_32x32x16_bf16 v[0:15], v[148:151], v[58:61], v[0:15]
	v_cvt_pk_bf16_f32 v52, v54, v56
	v_cvt_pk_bf16_f32 v53, v55, v57
	v_cvt_pk_bf16_f32 v32, v32, v48
	v_cvt_pk_bf16_f32 v33, v33, v49
	v_cvt_pk_bf16_f32 v34, v34, v36
	v_cvt_pk_bf16_f32 v35, v35, v37
	v_cvt_pk_bf16_f32 v36, v38, v40
	v_mfma_f32_32x32x16_bf16 v[16:31], v[120:123], v[58:61], v[16:31]
	v_cvt_pk_bf16_f32 v37, v39, v41
	v_cvt_pk_bf16_f32 v38, v42, v44
	v_cvt_pk_bf16_f32 v39, v43, v45
	s_and_b64 vcc, exec, s[14:15]
	v_mfma_f32_32x32x16_bf16 v[0:15], v[144:147], v[50:53], v[0:15]
	s_cbranch_vccnz .Lml_pk1
	s_and_b32 s16, s7, 3
	s_mulk_i32 s16, 0x5000
	s_add_i32 s16, s5, s16
	s_mov_b32 m0, s16
	s_nop 0
	global_load_lds_dwordx4 v[172:173], off
